# grid barrier: XCD leaders also watch the top-level arrival counter; the last leader needs no second atomic and the unused generation words are no longer bumped (leaders leave with the members)
# baseline (speedup 1.0000x reference)
; DI unsigned xb_ld(unsigned* p) { return __hip_atomic_load(p, __ATOMIC_RELAXED, __HIP_MEMORY_SCOPE_AGENT); }
; DI unsigned xb_add(unsigned* p, unsigned v) { return __hip_atomic_fetch_add(p, v, __ATOMIC_RELAXED, __HIP_MEMORY_SCOPE_AGENT); }
; #define XB_SPIN(cond, bar) do { unsigned _sp = 0; while (cond) { __builtin_amdgcn_s_sleep(1); \
;     if ((++_sp & 255u) == 0u) { if (xb_ld(&(bar)[XB_TMO])) break; if (_sp > XB_SPIN_CAP) { atomicAdd(&(bar)[XB_TMO], 1u); break; } } } } while (0)
; DI void xcd_barrier(const XcdBarrier& b) {
;     ...
;       const unsigned og = xb_add(&bar[XB_TOP], 1u);
;       const unsigned tg = og / nx;
;       if (og + 1u == (tg + 1u) * nx) xb_add(&bar[XB_TOPGEN], 1u);
;       else XB_SPIN(xb_ld(&bar[XB_TOPGEN]) == tg, bar);
.LBB0_296:
	s_or_b64 exec, exec, s[14:15]
	s_waitcnt vmcnt(0)
	v_readfirstlane_b32 s2, v4
	v_cvt_f32_u32_e32 v4, v2
	v_sub_u32_e32 v5, 0, v2
	v_add_u32_e32 v3, s2, v3
	s_add_u32 s12, s8, 0xfc9f400
	v_rcp_iflag_f32_e32 v4, v4
	s_addc_u32 s13, s9, 0
	s_mov_b64 s[18:19], -1
	v_mul_f32_e32 v4, 0x4f7ffffe, v4
	v_cvt_u32_f32_e32 v4, v4
	v_mul_lo_u32 v5, v5, v4
	v_mul_hi_u32 v5, v4, v5
	v_add_u32_e32 v4, v4, v5
	v_mul_hi_u32 v4, v3, v4
	v_mul_lo_u32 v5, v4, v2
	v_sub_u32_e32 v5, v3, v5
	v_cmp_ge_u32_e32 vcc, v5, v2
	v_add_u32_e32 v6, 1, v4
	v_add_u32_e32 v3, 1, v3
	v_cndmask_b32_e32 v4, v4, v6, vcc
	v_sub_u32_e32 v6, v5, v2
	v_cndmask_b32_e32 v5, v5, v6, vcc
	v_cmp_ge_u32_e32 vcc, v5, v2
	v_add_u32_e32 v5, 1, v4
	s_nop 0
	v_cndmask_b32_e32 v4, v4, v5, vcc
	v_mul_lo_u32 v5, v2, v4
	v_add_u32_e32 v2, v5, v2
	v_cmp_ne_u32_e32 vcc, v3, v2
	v_mov_b32_e32 v6, v2
	v_mov_b64_e32 v[2:3], s[12:13]
	s_and_saveexec_b64 s[14:15], vcc
	s_cbranch_execz .LBB0_308
	global_load_dword v2, v199, s[12:13] sc1
	s_mov_b64 s[24:25], 0
	s_waitcnt vmcnt(0)
	v_cmp_lt_u32_e32 vcc, v2, v6
	s_and_saveexec_b64 s[22:23], vcc
	s_cbranch_execz .LBB0_307
	s_add_u32 s18, s8, 0xfc9c200
	s_addc_u32 s19, s9, 0
	s_mov_b32 s2, 1
	s_mov_b64 s[8:9], 0
	s_branch .LBB0_300

; DI unsigned xb_ld(unsigned* p) { return __hip_atomic_load(p, __ATOMIC_RELAXED, __HIP_MEMORY_SCOPE_AGENT); }
; #define XB_SPIN(cond, bar) do { unsigned _sp = 0; while (cond) { __builtin_amdgcn_s_sleep(1); \
;     if ((++_sp & 255u) == 0u) { if (xb_ld(&(bar)[XB_TMO])) break; if (_sp > XB_SPIN_CAP) { atomicAdd(&(bar)[XB_TMO], 1u); break; } } } } while (0)
; DI void xcd_barrier(const XcdBarrier& b) {
;     ...
;       else XB_SPIN(xb_ld(&bar[XB_TOPGEN]) == tg, bar);
.LBB0_302:
	global_load_dword v2, v199, s[12:13] sc1
	s_add_i32 s2, s2, 1
	s_mov_b64 s[28:29], -1
	s_waitcnt vmcnt(0)
	v_cmp_ge_u32_e32 vcc, v2, v6
	s_orn2_b64 s[26:27], vcc, exec
	s_branch .LBB0_299

; DI unsigned xb_ld(unsigned* p) { return __hip_atomic_load(p, __ATOMIC_RELAXED, __HIP_MEMORY_SCOPE_AGENT); }
; DI unsigned xb_add(unsigned* p, unsigned v) { return __hip_atomic_fetch_add(p, v, __ATOMIC_RELAXED, __HIP_MEMORY_SCOPE_AGENT); }
; #define XB_SPIN(cond, bar) do { unsigned _sp = 0; while (cond) { __builtin_amdgcn_s_sleep(1); \
;     if ((++_sp & 255u) == 0u) { if (xb_ld(&(bar)[XB_TMO])) break; if (_sp > XB_SPIN_CAP) { atomicAdd(&(bar)[XB_TMO], 1u); break; } } } } while (0)
; DI void xcd_barrier(const XcdBarrier& b) {
;     ...
;       if (og + 1u == (tg + 1u) * nx) xb_add(&bar[XB_TOPGEN], 1u);
;       else XB_SPIN(xb_ld(&bar[XB_TOPGEN]) == tg, bar);
;       __builtin_amdgcn_fence(__ATOMIC_ACQUIRE, "agent");
;       xb_add(&bar[XB_XGEN(b.x)], 1u);
;       asm volatile("s_waitcnt vmcnt(0)" ::: "memory");
.LBB0_308:
	s_or_b64 exec, exec, s[14:15]
	s_and_saveexec_b64 s[8:9], s[18:19]
	s_cbranch_execz .LBB0_310
	v_mov_b32_e32 v4, 1
.LBB0_310:
	s_or_b64 exec, exec, s[8:9]
	s_mov_b64 s[8:9], exec
	v_mbcnt_lo_u32_b32 v2, s8, 0
	v_mbcnt_hi_u32_b32 v2, s9, v2
	v_cmp_eq_u32_e32 vcc, 0, v2
	s_waitcnt vmcnt(0)
	s_and_saveexec_b64 s[12:13], vcc
	s_cbranch_execz .LBB0_312
	s_bcnt1_i32_b64 s2, s[8:9]
	v_mov_b32_e32 v2, s2
.LBB0_312:
	s_or_b64 exec, exec, s[12:13]
	s_waitcnt vmcnt(0)

; DI unsigned xb_ld(unsigned* p) { return __hip_atomic_load(p, __ATOMIC_RELAXED, __HIP_MEMORY_SCOPE_AGENT); }
; DI unsigned xb_add(unsigned* p, unsigned v) { return __hip_atomic_fetch_add(p, v, __ATOMIC_RELAXED, __HIP_MEMORY_SCOPE_AGENT); }
; #define XB_SPIN(cond, bar) do { unsigned _sp = 0; while (cond) { __builtin_amdgcn_s_sleep(1); \
;     if ((++_sp & 255u) == 0u) { if (xb_ld(&(bar)[XB_TMO])) break; if (_sp > XB_SPIN_CAP) { atomicAdd(&(bar)[XB_TMO], 1u); break; } } } } while (0)
; DI void xcd_barrier(const XcdBarrier& b) {
;     ...
;       if (og + 1u == (tg + 1u) * nx) xb_add(&bar[XB_TOPGEN], 1u);
;       else XB_SPIN(xb_ld(&bar[XB_TOPGEN]) == tg, bar);
;       __builtin_amdgcn_fence(__ATOMIC_ACQUIRE, "agent");
;       xb_add(&bar[XB_XGEN(b.x)], 1u);
;       asm volatile("s_waitcnt vmcnt(0)" ::: "memory");
.LBB0_497:
	s_or_b64 exec, exec, s[14:15]
	s_and_saveexec_b64 s[8:9], s[18:19]
	s_cbranch_execz .LBB0_499
	v_mov_b32_e32 v4, 1
.LBB0_499:
	s_or_b64 exec, exec, s[8:9]
	s_mov_b64 s[8:9], exec
	v_mbcnt_lo_u32_b32 v2, s8, 0
	v_mbcnt_hi_u32_b32 v2, s9, v2
	v_cmp_eq_u32_e32 vcc, 0, v2
	s_waitcnt vmcnt(0)
	s_and_saveexec_b64 s[12:13], vcc
	s_cbranch_execz .LBB0_501
	s_bcnt1_i32_b64 s2, s[8:9]
	v_mov_b32_e32 v2, s2
.LBB0_501:
	s_or_b64 exec, exec, s[12:13]
	s_waitcnt vmcnt(0)

; DI unsigned xb_ld(unsigned* p) { return __hip_atomic_load(p, __ATOMIC_RELAXED, __HIP_MEMORY_SCOPE_AGENT); }
; DI unsigned xb_add(unsigned* p, unsigned v) { return __hip_atomic_fetch_add(p, v, __ATOMIC_RELAXED, __HIP_MEMORY_SCOPE_AGENT); }
; #define XB_SPIN(cond, bar) do { unsigned _sp = 0; while (cond) { __builtin_amdgcn_s_sleep(1); \
;     if ((++_sp & 255u) == 0u) { if (xb_ld(&(bar)[XB_TMO])) break; if (_sp > XB_SPIN_CAP) { atomicAdd(&(bar)[XB_TMO], 1u); break; } } } } while (0)
; DI void xcd_barrier(const XcdBarrier& b) {
;     ...
;       const unsigned og = xb_add(&bar[XB_TOP], 1u);
;       const unsigned tg = og / nx;
;       if (og + 1u == (tg + 1u) * nx) xb_add(&bar[XB_TOPGEN], 1u);
;       else XB_SPIN(xb_ld(&bar[XB_TOPGEN]) == tg, bar);
.LBB0_892:
	s_or_b64 exec, exec, s[14:15]
	s_waitcnt vmcnt(0)
	v_readfirstlane_b32 s2, v4
	v_cvt_f32_u32_e32 v4, v2
	v_sub_u32_e32 v5, 0, v2
	v_add_u32_e32 v3, s2, v3
	s_add_u32 s12, s8, 0xfc9f400
	v_rcp_iflag_f32_e32 v4, v4
	s_addc_u32 s13, s9, 0
	s_mov_b64 s[16:17], -1
	v_mul_f32_e32 v4, 0x4f7ffffe, v4
	v_cvt_u32_f32_e32 v4, v4
	v_mul_lo_u32 v5, v5, v4
	v_mul_hi_u32 v5, v4, v5
	v_add_u32_e32 v4, v4, v5
	v_mul_hi_u32 v4, v3, v4
	v_mul_lo_u32 v5, v4, v2
	v_sub_u32_e32 v5, v3, v5
	v_cmp_ge_u32_e32 vcc, v5, v2
	v_add_u32_e32 v6, 1, v4
	v_add_u32_e32 v3, 1, v3
	v_cndmask_b32_e32 v4, v4, v6, vcc
	v_sub_u32_e32 v6, v5, v2
	v_cndmask_b32_e32 v5, v5, v6, vcc
	v_cmp_ge_u32_e32 vcc, v5, v2
	v_add_u32_e32 v5, 1, v4
	s_nop 0
	v_cndmask_b32_e32 v4, v4, v5, vcc
	v_mul_lo_u32 v5, v2, v4
	v_add_u32_e32 v2, v5, v2
	v_cmp_ne_u32_e32 vcc, v3, v2
	v_mov_b32_e32 v6, v2
	v_mov_b64_e32 v[2:3], s[12:13]
	s_and_saveexec_b64 s[14:15], vcc
	s_cbranch_execz .LBB0_904
	global_load_dword v2, v199, s[12:13] sc1
	s_mov_b64 s[22:23], 0
	s_waitcnt vmcnt(0)
	v_cmp_lt_u32_e32 vcc, v2, v6
	s_and_saveexec_b64 s[18:19], vcc
	s_cbranch_execz .LBB0_903
	s_add_u32 s16, s8, 0xfc9c200
	s_addc_u32 s17, s9, 0
	s_mov_b32 s2, 1
	s_mov_b64 s[8:9], 0
	s_branch .LBB0_896

; DI unsigned xb_ld(unsigned* p) { return __hip_atomic_load(p, __ATOMIC_RELAXED, __HIP_MEMORY_SCOPE_AGENT); }
; #define XB_SPIN(cond, bar) do { unsigned _sp = 0; while (cond) { __builtin_amdgcn_s_sleep(1); \
;     if ((++_sp & 255u) == 0u) { if (xb_ld(&(bar)[XB_TMO])) break; if (_sp > XB_SPIN_CAP) { atomicAdd(&(bar)[XB_TMO], 1u); break; } } } } while (0)
; DI void xcd_barrier(const XcdBarrier& b) {
;     ...
;       else XB_SPIN(xb_ld(&bar[XB_TOPGEN]) == tg, bar);
.LBB0_898:
	global_load_dword v2, v199, s[12:13] sc1
	s_add_i32 s2, s2, 1
	s_mov_b64 s[26:27], -1
	s_waitcnt vmcnt(0)
	v_cmp_ge_u32_e32 vcc, v2, v6
	s_orn2_b64 s[24:25], vcc, exec
	s_branch .LBB0_895

; DI unsigned xb_ld(unsigned* p) { return __hip_atomic_load(p, __ATOMIC_RELAXED, __HIP_MEMORY_SCOPE_AGENT); }
; DI unsigned xb_add(unsigned* p, unsigned v) { return __hip_atomic_fetch_add(p, v, __ATOMIC_RELAXED, __HIP_MEMORY_SCOPE_AGENT); }
; #define XB_SPIN(cond, bar) do { unsigned _sp = 0; while (cond) { __builtin_amdgcn_s_sleep(1); \
;     if ((++_sp & 255u) == 0u) { if (xb_ld(&(bar)[XB_TMO])) break; if (_sp > XB_SPIN_CAP) { atomicAdd(&(bar)[XB_TMO], 1u); break; } } } } while (0)
; DI void xcd_barrier(const XcdBarrier& b) {
;     ...
;       if (og + 1u == (tg + 1u) * nx) xb_add(&bar[XB_TOPGEN], 1u);
;       else XB_SPIN(xb_ld(&bar[XB_TOPGEN]) == tg, bar);
;       __builtin_amdgcn_fence(__ATOMIC_ACQUIRE, "agent");
;       xb_add(&bar[XB_XGEN(b.x)], 1u);
;       asm volatile("s_waitcnt vmcnt(0)" ::: "memory");
.LBB0_904:
	s_or_b64 exec, exec, s[14:15]
	s_and_saveexec_b64 s[8:9], s[16:17]
	s_cbranch_execz .LBB0_906
	v_mov_b32_e32 v4, 1
.LBB0_906:
	s_or_b64 exec, exec, s[8:9]
	s_mov_b64 s[8:9], exec
	v_mbcnt_lo_u32_b32 v2, s8, 0
	v_mbcnt_hi_u32_b32 v2, s9, v2
	v_cmp_eq_u32_e32 vcc, 0, v2
	s_waitcnt vmcnt(0)
	s_and_saveexec_b64 s[12:13], vcc
	s_cbranch_execz .LBB0_908
	s_bcnt1_i32_b64 s2, s[8:9]
	v_mov_b32_e32 v2, s2
.LBB0_908:
	s_or_b64 exec, exec, s[12:13]
	s_waitcnt vmcnt(0)

; DI unsigned xb_ld(unsigned* p) { return __hip_atomic_load(p, __ATOMIC_RELAXED, __HIP_MEMORY_SCOPE_AGENT); }
; DI unsigned xb_add(unsigned* p, unsigned v) { return __hip_atomic_fetch_add(p, v, __ATOMIC_RELAXED, __HIP_MEMORY_SCOPE_AGENT); }
; #define XB_SPIN(cond, bar) do { unsigned _sp = 0; while (cond) { __builtin_amdgcn_s_sleep(1); \
;     if ((++_sp & 255u) == 0u) { if (xb_ld(&(bar)[XB_TMO])) break; if (_sp > XB_SPIN_CAP) { atomicAdd(&(bar)[XB_TMO], 1u); break; } } } } while (0)
; DI void xcd_barrier(const XcdBarrier& b) {
;     ...
;       if (og + 1u == (tg + 1u) * nx) xb_add(&bar[XB_TOPGEN], 1u);
;       else XB_SPIN(xb_ld(&bar[XB_TOPGEN]) == tg, bar);
;       __builtin_amdgcn_fence(__ATOMIC_ACQUIRE, "agent");
;       xb_add(&bar[XB_XGEN(b.x)], 1u);
;       asm volatile("s_waitcnt vmcnt(0)" ::: "memory");
.LBB0_1147:
	s_or_b64 exec, exec, s[14:15]
	s_and_saveexec_b64 s[8:9], s[16:17]
	s_cbranch_execz .LBB0_1149
	v_mov_b32_e32 v4, 1
.LBB0_1149:
	s_or_b64 exec, exec, s[8:9]
	s_mov_b64 s[8:9], exec
	v_mbcnt_lo_u32_b32 v2, s8, 0
	v_mbcnt_hi_u32_b32 v2, s9, v2
	v_cmp_eq_u32_e32 vcc, 0, v2
	s_waitcnt vmcnt(0)
	s_and_saveexec_b64 s[12:13], vcc
	s_cbranch_execz .LBB0_1151
	s_bcnt1_i32_b64 s2, s[8:9]
	v_mov_b32_e32 v2, s2
.LBB0_1151:
	s_or_b64 exec, exec, s[12:13]
	s_waitcnt vmcnt(0)

; DI unsigned xb_ld(unsigned* p) { return __hip_atomic_load(p, __ATOMIC_RELAXED, __HIP_MEMORY_SCOPE_AGENT); }
; DI unsigned xb_add(unsigned* p, unsigned v) { return __hip_atomic_fetch_add(p, v, __ATOMIC_RELAXED, __HIP_MEMORY_SCOPE_AGENT); }
; #define XB_SPIN(cond, bar) do { unsigned _sp = 0; while (cond) { __builtin_amdgcn_s_sleep(1); \
;     if ((++_sp & 255u) == 0u) { if (xb_ld(&(bar)[XB_TMO])) break; if (_sp > XB_SPIN_CAP) { atomicAdd(&(bar)[XB_TMO], 1u); break; } } } } while (0)
; DI void xcd_barrier(const XcdBarrier& b) {
;     ...
;       if (og + 1u == (tg + 1u) * nx) xb_add(&bar[XB_TOPGEN], 1u);
;       else XB_SPIN(xb_ld(&bar[XB_TOPGEN]) == tg, bar);
;       __builtin_amdgcn_fence(__ATOMIC_ACQUIRE, "agent");
;       xb_add(&bar[XB_XGEN(b.x)], 1u);
;       asm volatile("s_waitcnt vmcnt(0)" ::: "memory");
.LBB0_1701:
	s_or_b64 exec, exec, s[14:15]
	s_and_saveexec_b64 s[8:9], s[16:17]
	s_cbranch_execz .LBB0_1703
	v_mov_b32_e32 v4, 1
.LBB0_1703:
	s_or_b64 exec, exec, s[8:9]
	s_mov_b64 s[8:9], exec
	v_mbcnt_lo_u32_b32 v2, s8, 0
	v_mbcnt_hi_u32_b32 v2, s9, v2
	v_cmp_eq_u32_e32 vcc, 0, v2
	s_waitcnt vmcnt(0)
	s_and_saveexec_b64 s[12:13], vcc
	s_cbranch_execz .LBB0_1705
	s_bcnt1_i32_b64 s2, s[8:9]
	v_mov_b32_e32 v2, s2
.LBB0_1705:
	s_or_b64 exec, exec, s[12:13]
	s_waitcnt vmcnt(0)

; DI unsigned xb_ld(unsigned* p) { return __hip_atomic_load(p, __ATOMIC_RELAXED, __HIP_MEMORY_SCOPE_AGENT); }
; DI unsigned xb_add(unsigned* p, unsigned v) { return __hip_atomic_fetch_add(p, v, __ATOMIC_RELAXED, __HIP_MEMORY_SCOPE_AGENT); }
; #define XB_SPIN(cond, bar) do { unsigned _sp = 0; while (cond) { __builtin_amdgcn_s_sleep(1); \
;     if ((++_sp & 255u) == 0u) { if (xb_ld(&(bar)[XB_TMO])) break; if (_sp > XB_SPIN_CAP) { atomicAdd(&(bar)[XB_TMO], 1u); break; } } } } while (0)
; DI void xcd_barrier(const XcdBarrier& b) {
;     ...
;       if (og + 1u == (tg + 1u) * nx) xb_add(&bar[XB_TOPGEN], 1u);
;       else XB_SPIN(xb_ld(&bar[XB_TOPGEN]) == tg, bar);
;       __builtin_amdgcn_fence(__ATOMIC_ACQUIRE, "agent");
;       xb_add(&bar[XB_XGEN(b.x)], 1u);
;       asm volatile("s_waitcnt vmcnt(0)" ::: "memory");
.LBB0_1777:
	s_or_b64 exec, exec, s[14:15]
	s_and_saveexec_b64 s[8:9], s[16:17]
	s_cbranch_execz .LBB0_1779
	v_mov_b32_e32 v4, 1
.LBB0_1779:
	s_or_b64 exec, exec, s[8:9]
	s_mov_b64 s[8:9], exec
	v_mbcnt_lo_u32_b32 v2, s8, 0
	v_mbcnt_hi_u32_b32 v2, s9, v2
	v_cmp_eq_u32_e32 vcc, 0, v2
	s_waitcnt vmcnt(0)
	s_and_saveexec_b64 s[12:13], vcc
	s_cbranch_execz .LBB0_1781
	s_bcnt1_i32_b64 s2, s[8:9]
	v_mov_b32_e32 v2, s2
.LBB0_1781:
	s_or_b64 exec, exec, s[12:13]
	s_waitcnt vmcnt(0)

; DI unsigned xb_ld(unsigned* p) { return __hip_atomic_load(p, __ATOMIC_RELAXED, __HIP_MEMORY_SCOPE_AGENT); }
; DI unsigned xb_add(unsigned* p, unsigned v) { return __hip_atomic_fetch_add(p, v, __ATOMIC_RELAXED, __HIP_MEMORY_SCOPE_AGENT); }
; #define XB_SPIN(cond, bar) do { unsigned _sp = 0; while (cond) { __builtin_amdgcn_s_sleep(1); \
;     if ((++_sp & 255u) == 0u) { if (xb_ld(&(bar)[XB_TMO])) break; if (_sp > XB_SPIN_CAP) { atomicAdd(&(bar)[XB_TMO], 1u); break; } } } } while (0)
; DI void xcd_barrier(const XcdBarrier& b) {
;     ...
;       const unsigned og = xb_add(&bar[XB_TOP], 1u);
;       const unsigned tg = og / nx;
;       if (og + 1u == (tg + 1u) * nx) xb_add(&bar[XB_TOPGEN], 1u);
;       else XB_SPIN(xb_ld(&bar[XB_TOPGEN]) == tg, bar);
.LBB0_1836:
	s_or_b64 exec, exec, s[18:19]
	s_waitcnt vmcnt(0)
	v_readfirstlane_b32 s2, v4
	v_cvt_f32_u32_e32 v4, v2
	v_sub_u32_e32 v5, 0, v2
	v_add_u32_e32 v3, s2, v3
	s_add_u32 s16, s12, 0xfc9f400
	v_rcp_iflag_f32_e32 v4, v4
	s_addc_u32 s17, s13, 0
	s_mov_b64 s[22:23], -1
	v_mul_f32_e32 v4, 0x4f7ffffe, v4
	v_cvt_u32_f32_e32 v4, v4
	v_mul_lo_u32 v5, v5, v4
	v_mul_hi_u32 v5, v4, v5
	v_add_u32_e32 v4, v4, v5
	v_mul_hi_u32 v4, v3, v4
	v_mul_lo_u32 v5, v4, v2
	v_sub_u32_e32 v5, v3, v5
	v_cmp_ge_u32_e32 vcc, v5, v2
	v_add_u32_e32 v6, 1, v4
	v_add_u32_e32 v3, 1, v3
	v_cndmask_b32_e32 v4, v4, v6, vcc
	v_sub_u32_e32 v6, v5, v2
	v_cndmask_b32_e32 v5, v5, v6, vcc
	v_cmp_ge_u32_e32 vcc, v5, v2
	v_add_u32_e32 v5, 1, v4
	s_nop 0
	v_cndmask_b32_e32 v4, v4, v5, vcc
	v_mul_lo_u32 v5, v2, v4
	v_add_u32_e32 v2, v5, v2
	v_cmp_ne_u32_e32 vcc, v3, v2
	v_mov_b32_e32 v6, v2
	v_mov_b64_e32 v[2:3], s[16:17]
	s_and_saveexec_b64 s[18:19], vcc
	s_cbranch_execz .LBB0_1848
	global_load_dword v2, v199, s[16:17] sc1
	s_mov_b64 s[26:27], 0
	s_waitcnt vmcnt(0)
	v_cmp_lt_u32_e32 vcc, v2, v6
	s_and_saveexec_b64 s[24:25], vcc
	s_cbranch_execz .LBB0_1847
	s_add_u32 s22, s12, 0xfc9c200
	s_addc_u32 s23, s13, 0
	s_mov_b32 s2, 1
	s_mov_b64 s[12:13], 0
	s_branch .LBB0_1840

; DI unsigned xb_ld(unsigned* p) { return __hip_atomic_load(p, __ATOMIC_RELAXED, __HIP_MEMORY_SCOPE_AGENT); }
; #define XB_SPIN(cond, bar) do { unsigned _sp = 0; while (cond) { __builtin_amdgcn_s_sleep(1); \
;     if ((++_sp & 255u) == 0u) { if (xb_ld(&(bar)[XB_TMO])) break; if (_sp > XB_SPIN_CAP) { atomicAdd(&(bar)[XB_TMO], 1u); break; } } } } while (0)
; DI void xcd_barrier(const XcdBarrier& b) {
;     ...
;       else XB_SPIN(xb_ld(&bar[XB_TOPGEN]) == tg, bar);
.LBB0_1842:
	global_load_dword v2, v199, s[16:17] sc1
	s_add_i32 s2, s2, 1
	s_mov_b64 s[34:35], -1
	s_waitcnt vmcnt(0)
	v_cmp_ge_u32_e32 vcc, v2, v6
	s_orn2_b64 s[28:29], vcc, exec
	s_branch .LBB0_1839

; DI unsigned xb_ld(unsigned* p) { return __hip_atomic_load(p, __ATOMIC_RELAXED, __HIP_MEMORY_SCOPE_AGENT); }
; DI unsigned xb_add(unsigned* p, unsigned v) { return __hip_atomic_fetch_add(p, v, __ATOMIC_RELAXED, __HIP_MEMORY_SCOPE_AGENT); }
; #define XB_SPIN(cond, bar) do { unsigned _sp = 0; while (cond) { __builtin_amdgcn_s_sleep(1); \
;     if ((++_sp & 255u) == 0u) { if (xb_ld(&(bar)[XB_TMO])) break; if (_sp > XB_SPIN_CAP) { atomicAdd(&(bar)[XB_TMO], 1u); break; } } } } while (0)
; DI void xcd_barrier(const XcdBarrier& b) {
;     ...
;       if (og + 1u == (tg + 1u) * nx) xb_add(&bar[XB_TOPGEN], 1u);
;       else XB_SPIN(xb_ld(&bar[XB_TOPGEN]) == tg, bar);
;       __builtin_amdgcn_fence(__ATOMIC_ACQUIRE, "agent");
;       xb_add(&bar[XB_XGEN(b.x)], 1u);
;       asm volatile("s_waitcnt vmcnt(0)" ::: "memory");
.LBB0_1848:
	s_or_b64 exec, exec, s[18:19]
	s_and_saveexec_b64 s[12:13], s[22:23]
	s_cbranch_execz .LBB0_1850
	v_mov_b32_e32 v4, 1
.LBB0_1850:
	s_or_b64 exec, exec, s[12:13]
	s_mov_b64 s[12:13], exec
	v_mbcnt_lo_u32_b32 v2, s12, 0
	v_mbcnt_hi_u32_b32 v2, s13, v2
	v_cmp_eq_u32_e32 vcc, 0, v2
	s_waitcnt vmcnt(0)
	s_and_saveexec_b64 s[16:17], vcc
	s_cbranch_execz .LBB0_1852
	s_bcnt1_i32_b64 s2, s[12:13]
	v_mov_b32_e32 v2, s2
.LBB0_1852:
	s_or_b64 exec, exec, s[16:17]
	s_waitcnt vmcnt(0)

; DI unsigned xb_ld(unsigned* p) { return __hip_atomic_load(p, __ATOMIC_RELAXED, __HIP_MEMORY_SCOPE_AGENT); }
; DI unsigned xb_add(unsigned* p, unsigned v) { return __hip_atomic_fetch_add(p, v, __ATOMIC_RELAXED, __HIP_MEMORY_SCOPE_AGENT); }
; #define XB_SPIN(cond, bar) do { unsigned _sp = 0; while (cond) { __builtin_amdgcn_s_sleep(1); \
;     if ((++_sp & 255u) == 0u) { if (xb_ld(&(bar)[XB_TMO])) break; if (_sp > XB_SPIN_CAP) { atomicAdd(&(bar)[XB_TMO], 1u); break; } } } } while (0)
; DI void xcd_barrier(const XcdBarrier& b) {
;     ...
;       if (og + 1u == (tg + 1u) * nx) xb_add(&bar[XB_TOPGEN], 1u);
;       else XB_SPIN(xb_ld(&bar[XB_TOPGEN]) == tg, bar);
;       __builtin_amdgcn_fence(__ATOMIC_ACQUIRE, "agent");
;       xb_add(&bar[XB_XGEN(b.x)], 1u);
;       asm volatile("s_waitcnt vmcnt(0)" ::: "memory");
.LBB0_1915:
	s_or_b64 exec, exec, s[18:19]
	s_and_saveexec_b64 s[12:13], s[22:23]
	s_cbranch_execz .LBB0_1917
	v_mov_b32_e32 v4, 1
.LBB0_1917:
	s_or_b64 exec, exec, s[12:13]
	s_mov_b64 s[12:13], exec
	v_mbcnt_lo_u32_b32 v2, s12, 0
	v_mbcnt_hi_u32_b32 v2, s13, v2
	v_cmp_eq_u32_e32 vcc, 0, v2
	s_waitcnt vmcnt(0)
	s_and_saveexec_b64 s[16:17], vcc
	s_cbranch_execz .LBB0_1919
	s_bcnt1_i32_b64 s2, s[12:13]
	v_mov_b32_e32 v2, s2
.LBB0_1919:
	s_or_b64 exec, exec, s[16:17]
	s_waitcnt vmcnt(0)

; DI unsigned xb_ld(unsigned* p) { return __hip_atomic_load(p, __ATOMIC_RELAXED, __HIP_MEMORY_SCOPE_AGENT); }
; DI unsigned xb_add(unsigned* p, unsigned v) { return __hip_atomic_fetch_add(p, v, __ATOMIC_RELAXED, __HIP_MEMORY_SCOPE_AGENT); }
; #define XB_SPIN(cond, bar) do { unsigned _sp = 0; while (cond) { __builtin_amdgcn_s_sleep(1); \
;     if ((++_sp & 255u) == 0u) { if (xb_ld(&(bar)[XB_TMO])) break; if (_sp > XB_SPIN_CAP) { atomicAdd(&(bar)[XB_TMO], 1u); break; } } } } while (0)
; DI void xcd_barrier(const XcdBarrier& b) {
;     ...
;       if (og + 1u == (tg + 1u) * nx) xb_add(&bar[XB_TOPGEN], 1u);
;       else XB_SPIN(xb_ld(&bar[XB_TOPGEN]) == tg, bar);
;       __builtin_amdgcn_fence(__ATOMIC_ACQUIRE, "agent");
;       xb_add(&bar[XB_XGEN(b.x)], 1u);
;       asm volatile("s_waitcnt vmcnt(0)" ::: "memory");
.LBB0_1998:
	s_or_b64 exec, exec, s[18:19]
	s_and_saveexec_b64 s[12:13], s[22:23]
	s_cbranch_execz .LBB0_2000
	v_mov_b32_e32 v4, 1
.LBB0_2000:
	s_or_b64 exec, exec, s[12:13]
	s_mov_b64 s[12:13], exec
	v_mbcnt_lo_u32_b32 v2, s12, 0
	v_mbcnt_hi_u32_b32 v2, s13, v2
	v_cmp_eq_u32_e32 vcc, 0, v2
	s_waitcnt vmcnt(0)
	s_and_saveexec_b64 s[16:17], vcc
	s_cbranch_execz .LBB0_2002
	s_bcnt1_i32_b64 s2, s[12:13]
	v_mov_b32_e32 v2, s2
.LBB0_2002:
	s_or_b64 exec, exec, s[16:17]
	s_waitcnt vmcnt(0)

; DI unsigned xb_ld(unsigned* p) { return __hip_atomic_load(p, __ATOMIC_RELAXED, __HIP_MEMORY_SCOPE_AGENT); }
; DI unsigned xb_add(unsigned* p, unsigned v) { return __hip_atomic_fetch_add(p, v, __ATOMIC_RELAXED, __HIP_MEMORY_SCOPE_AGENT); }
; #define XB_SPIN(cond, bar) do { unsigned _sp = 0; while (cond) { __builtin_amdgcn_s_sleep(1); \
;     if ((++_sp & 255u) == 0u) { if (xb_ld(&(bar)[XB_TMO])) break; if (_sp > XB_SPIN_CAP) { atomicAdd(&(bar)[XB_TMO], 1u); break; } } } } while (0)
; DI void xcd_barrier(const XcdBarrier& b) {
;     ...
;       if (og + 1u == (tg + 1u) * nx) xb_add(&bar[XB_TOPGEN], 1u);
;       else XB_SPIN(xb_ld(&bar[XB_TOPGEN]) == tg, bar);
;       __builtin_amdgcn_fence(__ATOMIC_ACQUIRE, "agent");
;       xb_add(&bar[XB_XGEN(b.x)], 1u);
;       asm volatile("s_waitcnt vmcnt(0)" ::: "memory");
.LBB0_2068:
	s_or_b64 exec, exec, s[14:15]
	s_and_saveexec_b64 s[8:9], s[16:17]
	s_cbranch_execz .LBB0_2070
	v_mov_b32_e32 v4, 1
.LBB0_2070:
	s_or_b64 exec, exec, s[8:9]
	s_mov_b64 s[8:9], exec
	v_mbcnt_lo_u32_b32 v2, s8, 0
	v_mbcnt_hi_u32_b32 v2, s9, v2
	v_cmp_eq_u32_e32 vcc, 0, v2
	s_waitcnt vmcnt(0)
	s_and_saveexec_b64 s[12:13], vcc
	s_cbranch_execnz .LBB0_2071
	s_getpc_b64 s[98:99]

; DI unsigned xb_add(unsigned* p, unsigned v) { return __hip_atomic_fetch_add(p, v, __ATOMIC_RELAXED, __HIP_MEMORY_SCOPE_AGENT); }
; DI void xcd_barrier(const XcdBarrier& b) {
;     ...
;       xb_add(&bar[XB_XGEN(b.x)], 1u);
.LBB0_2071:
	s_bcnt1_i32_b64 s2, s[8:9]
	v_mov_b32_e32 v2, s2
	s_getpc_b64 s[98:99]
